# layer-0 w_in GEMM: XCD-contiguous enumeration with exactly one 8x24 tile group per XCD, and the split round made of the 96 context-row tiles (each XCD one row tile x 12 column tiles) instead of scatte
# speedup vs baseline: 1.0037x; 1.0037x over previous
.Lgi_sk_rm0:
	s_and_b32 s0, s57, 7
	s_lshr_b32 s1, s57, 3
	s_mul_i32 s0, s0, 192
	s_add_u32 s57, s0, s1
	s_branch .Lgi_sk_inv
